# GEMM K-loop: M0 no longer saved and restored around each LDS-DMA issue (nothing else reads M0)
# baseline (speedup 1.0000x reference)
; #define PG8_STAGE(bufoff, gbase, voff) do { _Pragma("unroll") for (int _i = 0; _i < 2; ++_i) \
;         glds16((const void*)(gbase), (voff)[_i], (unsigned)__builtin_amdgcn_readfirstlane(lds0 + (bufoff) + ldsw + _i * 8192)); } while (0)
; #define PG8_LDA(dst, b, h) do { _Pragma("unroll") for (int m = 0; m < 4; ++m) _Pragma("unroll") for (int k = 0; k < 2; ++k) dst[m][k] = *(const LAS bf16x8*)(lds + PG8_SA(b, h) + aoff + m * 2048 + k * 1024); } while (0)
; #define PG8_LDB(dst, b, h) do { _Pragma("unroll") for (int n = 0; n < 2; ++n) _Pragma("unroll") for (int k = 0; k < 2; ++k) dst[n][k] = *(const LAS bf16x8*)(lds + PG8_SB(b, h) + boff + n * 2048 + k * 1024); } while (0)
; #define PG8_MMA(ai, bj, At, Bt) do { __builtin_amdgcn_s_setprio(1); _Pragma("unroll") for (int m = 0; m < 4; ++m) _Pragma("unroll") for (int n = 0; n < 2; ++n) _Pragma("unroll") for (int k = 0; k < 2; ++k) \
;         acc[ai][bj][m][n] = __builtin_amdgcn_mfma_f32_16x16x32_bf16(Bt[n][k], At[m][k], acc[ai][bj][m][n], 0, 0, 0); __builtin_amdgcn_s_setprio(0); } while (0)
; #define PG8_WAIT_V(n) asm volatile("s_waitcnt vmcnt(" #n ")" ::: "memory")
; #define PG8_WAIT_L(n) asm volatile("s_waitcnt lgkmcnt(" #n ")" ::: "memory")
; #define PG8_BAR __builtin_amdgcn_s_barrier()
; #define PG8_SCHED __builtin_amdgcn_sched_barrier(0)
; __device__ __forceinline__ void glds16(const void* gbase, unsigned voff, unsigned lds_dst) { unsigned keep;
;     asm volatile("s_mov_b32 %0, m0\n\ts_mov_b32 m0, %3\n\ts_nop 0\n\tglobal_load_lds_dwordx4 %1, %2\n\ts_mov_b32 m0, %0" : "=&s"(keep) : "v"(voff), "s"(gbase), "s"(lds_dst) : "memory"); }
; template <class Epi, class Sched, bool ALIGN_EPI = false, bool SP2 = false>
; __device__ __forceinline__ void gemm_phase(LAS unsigned char* lds, const Gemm g, const Sched& S, const Epi& E) {
;     ...
;             PG8_LDB(B0, 0, 0); PG8_LDB(B1, 0, 1); PG8_SCHED; PG8_LDA(At, 0, 0); PG8_STAGE(PG8_SA(1, 1), a1 + hstep, voffA);
;             PG8_WAIT_V(8); PG8_WAIT_L(0); PG8_BAR; PG8_MMA(0, 0, At, B0); PG8_MMA(0, 1, At, B1); PG8_BAR; PG8_SCHED;
;             PG8_LDA(At, 0, 1); PG8_STAGE(PG8_SB(0, 0), b2, voffB); PG8_STAGE(PG8_SB(0, 1), b2 + hstep, voffB); PG8_STAGE(PG8_SA(0, 0), a2, voffA);
;             PG8_WAIT_V(8); PG8_WAIT_L(0); PG8_BAR; PG8_MMA(1, 0, At, B0); PG8_MMA(1, 1, At, B1); PG8_BAR; PG8_SCHED;
.LBB0_117:
	ds_read_b128 v[132:135], v153
	ds_read_b128 v[136:139], v153 offset:1024
	ds_read_b128 v[142:145], v153 offset:2048
	ds_read_b128 v[168:171], v153 offset:3072
	ds_read_b128 v[172:175], v154
	ds_read_b128 v[176:179], v154 offset:1024
	ds_read_b128 v[180:183], v154 offset:2048
	ds_read_b128 v[184:187], v154 offset:3072
	s_add_u32 vcc_lo, s22, 0x100
	s_addc_u32 vcc_hi, s23, 0
	s_cmp_eq_u32 s77, 12
	s_cselect_b32 s10, s73, vcc_lo
	s_cselect_b32 s11, s29, vcc_hi
	s_cselect_b32 s46, s74, s75
	s_cselect_b32 s47, s13, s76
	s_add_u32 s82, s10, 0x80
	s_addc_u32 s83, s11, 0
	ds_read_b128 v[188:191], v155
	ds_read_b128 v[192:195], v155 offset:1024
	ds_read_b128 v[196:199], v155 offset:2048
	ds_read_b128 v[200:203], v155 offset:3072
	ds_read_b128 v[204:207], v155 offset:4096
	ds_read_b128 v[208:211], v155 offset:5120
	ds_read_b128 v[212:215], v155 offset:6144
	ds_read_b128 v[216:219], v155 offset:7168
	s_add_u32 s22, s22, 0x40080
	s_addc_u32 s23, s23, 0
	s_mov_b32 m0, s71
	s_nop 0
	global_load_lds_dwordx4 v0, s[22:23]
	s_add_i32 s26, s2, 0xe000
	s_mov_b32 m0, s26
	s_nop 0
	global_load_lds_dwordx4 v149, s[22:23]
	s_waitcnt vmcnt(8)
	s_waitcnt lgkmcnt(0)
	s_barrier
	s_setprio 1
	s_waitcnt lgkmcnt(7)
	v_mfma_f32_16x16x32_bf16 v[126:129], v[132:135], v[188:191], v[126:129]
	v_mfma_f32_16x16x32_bf16 v[122:125], v[142:145], v[188:191], v[122:125]
	s_waitcnt lgkmcnt(5)
	v_mfma_f32_16x16x32_bf16 v[118:121], v[132:135], v[196:199], v[118:121]
	v_mfma_f32_16x16x32_bf16 v[110:113], v[142:145], v[196:199], v[110:113]
	s_waitcnt lgkmcnt(3)
	v_mfma_f32_16x16x32_bf16 v[102:105], v[132:135], v[204:207], v[102:105]
	v_mfma_f32_16x16x32_bf16 v[94:97], v[142:145], v[204:207], v[94:97]
	s_waitcnt lgkmcnt(1)
	v_mfma_f32_16x16x32_bf16 v[86:89], v[132:135], v[212:215], v[86:89]
	v_mfma_f32_16x16x32_bf16 v[78:81], v[142:145], v[212:215], v[78:81]
	v_mfma_f32_16x16x32_bf16 v[126:129], v[136:139], v[192:195], v[126:129]
	v_mfma_f32_16x16x32_bf16 v[122:125], v[168:171], v[192:195], v[122:125]
	v_mfma_f32_16x16x32_bf16 v[118:121], v[136:139], v[200:203], v[118:121]
	v_mfma_f32_16x16x32_bf16 v[110:113], v[168:171], v[200:203], v[110:113]
	v_mfma_f32_16x16x32_bf16 v[102:105], v[136:139], v[208:211], v[102:105]
	v_mfma_f32_16x16x32_bf16 v[94:97], v[168:171], v[208:211], v[94:97]
	s_waitcnt lgkmcnt(0)
	v_mfma_f32_16x16x32_bf16 v[86:89], v[136:139], v[216:219], v[86:89]
	v_mfma_f32_16x16x32_bf16 v[78:81], v[168:171], v[216:219], v[78:81]
	s_setprio 0
	s_setprio 1
	v_mfma_f32_16x16x32_bf16 v[114:117], v[172:175], v[188:191], v[114:117]
	v_mfma_f32_16x16x32_bf16 v[106:109], v[180:183], v[188:191], v[106:109]
	v_mfma_f32_16x16x32_bf16 v[98:101], v[172:175], v[196:199], v[98:101]
	v_mfma_f32_16x16x32_bf16 v[90:93], v[180:183], v[196:199], v[90:93]
	v_mfma_f32_16x16x32_bf16 v[82:85], v[172:175], v[204:207], v[82:85]
	v_mfma_f32_16x16x32_bf16 v[74:77], v[180:183], v[204:207], v[74:77]
	v_mfma_f32_16x16x32_bf16 v[70:73], v[172:175], v[212:215], v[70:73]
	v_mfma_f32_16x16x32_bf16 v[66:69], v[180:183], v[212:215], v[66:69]
	v_mfma_f32_16x16x32_bf16 v[114:117], v[176:179], v[192:195], v[114:117]
	v_mfma_f32_16x16x32_bf16 v[106:109], v[184:187], v[192:195], v[106:109]
	v_mfma_f32_16x16x32_bf16 v[98:101], v[176:179], v[200:203], v[98:101]
	v_mfma_f32_16x16x32_bf16 v[90:93], v[184:187], v[200:203], v[90:93]
	v_mfma_f32_16x16x32_bf16 v[82:85], v[176:179], v[208:211], v[82:85]
	v_mfma_f32_16x16x32_bf16 v[74:77], v[184:187], v[208:211], v[74:77]
	v_mfma_f32_16x16x32_bf16 v[70:73], v[176:179], v[216:219], v[70:73]
	v_mfma_f32_16x16x32_bf16 v[66:69], v[184:187], v[216:219], v[66:69]
	s_setprio 0
	s_barrier
	ds_read_b128 v[188:191], v155 offset:16384
	ds_read_b128 v[192:195], v155 offset:17408
	ds_read_b128 v[196:199], v155 offset:18432
	ds_read_b128 v[200:203], v155 offset:19456
	ds_read_b128 v[204:207], v155 offset:20480
	ds_read_b128 v[208:211], v155 offset:21504
	ds_read_b128 v[212:215], v155 offset:22528
	ds_read_b128 v[216:219], v155 offset:23552
	s_mov_b32 m0, s21
	s_nop 0
	global_load_lds_dwordx4 v148, s[46:47]
	s_nop 0
	s_mov_b32 m0, s56
	s_nop 0
	global_load_lds_dwordx4 v150, s[46:47]
	s_add_u32 s22, s46, 0x40000
	s_addc_u32 s23, s47, 0
	s_mov_b32 m0, s57
	s_nop 0
	global_load_lds_dwordx4 v148, s[22:23]
	s_nop 0
	s_mov_b32 m0, s58
	s_nop 0
	global_load_lds_dwordx4 v150, s[22:23]
	s_mov_b32 m0, s2
	s_nop 0
	global_load_lds_dwordx4 v0, s[10:11]
	s_nop 0
	s_mov_b32 m0, s59
	s_nop 0
	global_load_lds_dwordx4 v149, s[10:11]
	s_waitcnt vmcnt(8)
	s_waitcnt lgkmcnt(0)
	s_barrier
; #define PG8_STAGE(bufoff, gbase, voff) do { _Pragma("unroll") for (int _i = 0; _i < 2; ++_i) \
;         glds16((const void*)(gbase), (voff)[_i], (unsigned)__builtin_amdgcn_readfirstlane(lds0 + (bufoff) + ldsw + _i * 8192)); } while (0)
; #define PG8_LDA(dst, b, h) do { _Pragma("unroll") for (int m = 0; m < 4; ++m) _Pragma("unroll") for (int k = 0; k < 2; ++k) dst[m][k] = *(const LAS bf16x8*)(lds + PG8_SA(b, h) + aoff + m * 2048 + k * 1024); } while (0)
; #define PG8_LDB(dst, b, h) do { _Pragma("unroll") for (int n = 0; n < 2; ++n) _Pragma("unroll") for (int k = 0; k < 2; ++k) dst[n][k] = *(const LAS bf16x8*)(lds + PG8_SB(b, h) + boff + n * 2048 + k * 1024); } while (0)
; #define PG8_MMA(ai, bj, At, Bt) do { __builtin_amdgcn_s_setprio(1); _Pragma("unroll") for (int m = 0; m < 4; ++m) _Pragma("unroll") for (int n = 0; n < 2; ++n) _Pragma("unroll") for (int k = 0; k < 2; ++k) \
;         acc[ai][bj][m][n] = __builtin_amdgcn_mfma_f32_16x16x32_bf16(Bt[n][k], At[m][k], acc[ai][bj][m][n], 0, 0, 0); __builtin_amdgcn_s_setprio(0); } while (0)
; #define PG8_WAIT_V(n) asm volatile("s_waitcnt vmcnt(" #n ")" ::: "memory")
; #define PG8_WAIT_L(n) asm volatile("s_waitcnt lgkmcnt(" #n ")" ::: "memory")
; #define PG8_BAR __builtin_amdgcn_s_barrier()
; #define PG8_SCHED __builtin_amdgcn_sched_barrier(0)
; template <class Epi, class Sched, bool ALIGN_EPI = false, bool SP2 = false>
; __device__ __forceinline__ void gemm_phase(LAS unsigned char* lds, const Gemm g, const Sched& S, const Epi& E) {
;     ...
;             PG8_WAIT_V(8); PG8_WAIT_L(0); PG8_BAR; PG8_MMA(1, 0, At, B0); PG8_MMA(1, 1, At, B1); PG8_BAR; PG8_SCHED;
;             PG8_LDB(B0, 1, 0); PG8_LDB(B1, 1, 1); PG8_SCHED; PG8_LDA(At, 1, 0); PG8_STAGE(PG8_SA(0, 1), a2 + hstep, voffA);
;             PG8_WAIT_V(8); PG8_WAIT_L(0); PG8_BAR; PG8_MMA(0, 0, At, B0); PG8_MMA(0, 1, At, B1); PG8_BAR; PG8_SCHED;
	s_setprio 1
	s_waitcnt lgkmcnt(7)
	v_mfma_f32_16x16x32_bf16 v[62:65], v[132:135], v[188:191], v[62:65]
	v_mfma_f32_16x16x32_bf16 v[58:61], v[142:145], v[188:191], v[58:61]
	s_waitcnt lgkmcnt(5)
	v_mfma_f32_16x16x32_bf16 v[54:57], v[132:135], v[196:199], v[54:57]
	v_mfma_f32_16x16x32_bf16 v[46:49], v[142:145], v[196:199], v[46:49]
	s_waitcnt lgkmcnt(3)
	v_mfma_f32_16x16x32_bf16 v[38:41], v[132:135], v[204:207], v[38:41]
	v_mfma_f32_16x16x32_bf16 v[30:33], v[142:145], v[204:207], v[30:33]
	s_waitcnt lgkmcnt(1)
	v_mfma_f32_16x16x32_bf16 v[22:25], v[132:135], v[212:215], v[22:25]
	v_mfma_f32_16x16x32_bf16 v[14:17], v[142:145], v[212:215], v[14:17]
	v_mfma_f32_16x16x32_bf16 v[62:65], v[136:139], v[192:195], v[62:65]
	v_mfma_f32_16x16x32_bf16 v[58:61], v[168:171], v[192:195], v[58:61]
	v_mfma_f32_16x16x32_bf16 v[54:57], v[136:139], v[200:203], v[54:57]
	v_mfma_f32_16x16x32_bf16 v[46:49], v[168:171], v[200:203], v[46:49]
	v_mfma_f32_16x16x32_bf16 v[38:41], v[136:139], v[208:211], v[38:41]
	v_mfma_f32_16x16x32_bf16 v[30:33], v[168:171], v[208:211], v[30:33]
	s_waitcnt lgkmcnt(0)
	v_mfma_f32_16x16x32_bf16 v[22:25], v[136:139], v[216:219], v[22:25]
	v_mfma_f32_16x16x32_bf16 v[14:17], v[168:171], v[216:219], v[14:17]
	s_setprio 0
	s_setprio 1
	v_mfma_f32_16x16x32_bf16 v[50:53], v[172:175], v[188:191], v[50:53]
	v_mfma_f32_16x16x32_bf16 v[42:45], v[180:183], v[188:191], v[42:45]
	v_mfma_f32_16x16x32_bf16 v[34:37], v[172:175], v[196:199], v[34:37]
	v_mfma_f32_16x16x32_bf16 v[26:29], v[180:183], v[196:199], v[26:29]
	v_mfma_f32_16x16x32_bf16 v[18:21], v[172:175], v[204:207], v[18:21]
	v_mfma_f32_16x16x32_bf16 v[10:13], v[180:183], v[204:207], v[10:13]
	v_mfma_f32_16x16x32_bf16 v[6:9], v[172:175], v[212:215], v[6:9]
	v_mfma_f32_16x16x32_bf16 v[2:5], v[180:183], v[212:215], v[2:5]
	v_mfma_f32_16x16x32_bf16 v[50:53], v[176:179], v[192:195], v[50:53]
	v_mfma_f32_16x16x32_bf16 v[42:45], v[184:187], v[192:195], v[42:45]
	v_mfma_f32_16x16x32_bf16 v[34:37], v[176:179], v[200:203], v[34:37]
	v_mfma_f32_16x16x32_bf16 v[26:29], v[184:187], v[200:203], v[26:29]
	v_mfma_f32_16x16x32_bf16 v[18:21], v[176:179], v[208:211], v[18:21]
	v_mfma_f32_16x16x32_bf16 v[10:13], v[184:187], v[208:211], v[10:13]
	v_mfma_f32_16x16x32_bf16 v[6:9], v[176:179], v[216:219], v[6:9]
	v_mfma_f32_16x16x32_bf16 v[2:5], v[184:187], v[216:219], v[2:5]
	s_setprio 0
	s_barrier
	ds_read_b128 v[132:135], v156
	ds_read_b128 v[136:139], v156 offset:1024
	ds_read_b128 v[142:145], v156 offset:2048
	ds_read_b128 v[168:171], v156 offset:3072
	ds_read_b128 v[172:175], v157
	ds_read_b128 v[176:179], v157 offset:1024
	ds_read_b128 v[180:183], v157 offset:2048
	ds_read_b128 v[184:187], v157 offset:3072
	ds_read_b128 v[188:191], v155 offset:32768
	ds_read_b128 v[192:195], v155 offset:33792
	ds_read_b128 v[196:199], v155 offset:34816
	ds_read_b128 v[200:203], v155 offset:35840
	ds_read_b128 v[204:207], v155 offset:36864
	ds_read_b128 v[208:211], v155 offset:37888
	ds_read_b128 v[212:215], v155 offset:38912
	ds_read_b128 v[216:219], v155 offset:39936
	s_add_u32 s10, s10, 0x40000
	s_addc_u32 s11, s11, 0
	s_mov_b32 m0, s60
	s_nop 0
	global_load_lds_dwordx4 v0, s[10:11]
	s_nop 0
	s_mov_b32 m0, s61
	s_nop 0
	global_load_lds_dwordx4 v149, s[10:11]
	s_waitcnt vmcnt(8)
	s_waitcnt lgkmcnt(0)
	s_barrier
	s_setprio 1
	s_waitcnt lgkmcnt(7)
	v_mfma_f32_16x16x32_bf16 v[126:129], v[132:135], v[188:191], v[126:129]
	v_mfma_f32_16x16x32_bf16 v[122:125], v[142:145], v[188:191], v[122:125]
	s_waitcnt lgkmcnt(5)
	v_mfma_f32_16x16x32_bf16 v[118:121], v[132:135], v[196:199], v[118:121]
	v_mfma_f32_16x16x32_bf16 v[110:113], v[142:145], v[196:199], v[110:113]
	s_waitcnt lgkmcnt(3)
	v_mfma_f32_16x16x32_bf16 v[102:105], v[132:135], v[204:207], v[102:105]
	v_mfma_f32_16x16x32_bf16 v[94:97], v[142:145], v[204:207], v[94:97]
	s_waitcnt lgkmcnt(1)
	v_mfma_f32_16x16x32_bf16 v[86:89], v[132:135], v[212:215], v[86:89]
	v_mfma_f32_16x16x32_bf16 v[78:81], v[142:145], v[212:215], v[78:81]
	v_mfma_f32_16x16x32_bf16 v[126:129], v[136:139], v[192:195], v[126:129]
	v_mfma_f32_16x16x32_bf16 v[122:125], v[168:171], v[192:195], v[122:125]
	v_mfma_f32_16x16x32_bf16 v[118:121], v[136:139], v[200:203], v[118:121]
	v_mfma_f32_16x16x32_bf16 v[110:113], v[168:171], v[200:203], v[110:113]
	v_mfma_f32_16x16x32_bf16 v[102:105], v[136:139], v[208:211], v[102:105]
	v_mfma_f32_16x16x32_bf16 v[94:97], v[168:171], v[208:211], v[94:97]
	s_waitcnt lgkmcnt(0)
	v_mfma_f32_16x16x32_bf16 v[86:89], v[136:139], v[216:219], v[86:89]
	v_mfma_f32_16x16x32_bf16 v[78:81], v[168:171], v[216:219], v[78:81]
	s_setprio 0
	s_setprio 1
	v_mfma_f32_16x16x32_bf16 v[114:117], v[172:175], v[188:191], v[114:117]
	v_mfma_f32_16x16x32_bf16 v[106:109], v[180:183], v[188:191], v[106:109]
	v_mfma_f32_16x16x32_bf16 v[98:101], v[172:175], v[196:199], v[98:101]
	v_mfma_f32_16x16x32_bf16 v[90:93], v[180:183], v[196:199], v[90:93]
	v_mfma_f32_16x16x32_bf16 v[82:85], v[172:175], v[204:207], v[82:85]
	v_mfma_f32_16x16x32_bf16 v[74:77], v[180:183], v[204:207], v[74:77]
	v_mfma_f32_16x16x32_bf16 v[70:73], v[172:175], v[212:215], v[70:73]
	v_mfma_f32_16x16x32_bf16 v[66:69], v[180:183], v[212:215], v[66:69]
	v_mfma_f32_16x16x32_bf16 v[114:117], v[176:179], v[192:195], v[114:117]
	v_mfma_f32_16x16x32_bf16 v[106:109], v[184:187], v[192:195], v[106:109]
	v_mfma_f32_16x16x32_bf16 v[98:101], v[176:179], v[200:203], v[98:101]
	v_mfma_f32_16x16x32_bf16 v[90:93], v[184:187], v[200:203], v[90:93]
	v_mfma_f32_16x16x32_bf16 v[82:85], v[176:179], v[208:211], v[82:85]
	v_mfma_f32_16x16x32_bf16 v[74:77], v[184:187], v[208:211], v[74:77]
	v_mfma_f32_16x16x32_bf16 v[70:73], v[176:179], v[216:219], v[70:73]
	v_mfma_f32_16x16x32_bf16 v[66:69], v[184:187], v[216:219], v[66:69]
	s_setprio 0
	s_barrier
; #define PG8_STAGE(bufoff, gbase, voff) do { _Pragma("unroll") for (int _i = 0; _i < 2; ++_i) \
;         glds16((const void*)(gbase), (voff)[_i], (unsigned)__builtin_amdgcn_readfirstlane(lds0 + (bufoff) + ldsw + _i * 8192)); } while (0)
; #define PG8_LDA(dst, b, h) do { _Pragma("unroll") for (int m = 0; m < 4; ++m) _Pragma("unroll") for (int k = 0; k < 2; ++k) dst[m][k] = *(const LAS bf16x8*)(lds + PG8_SA(b, h) + aoff + m * 2048 + k * 1024); } while (0)
; #define PG8_MMA(ai, bj, At, Bt) do { __builtin_amdgcn_s_setprio(1); _Pragma("unroll") for (int m = 0; m < 4; ++m) _Pragma("unroll") for (int n = 0; n < 2; ++n) _Pragma("unroll") for (int k = 0; k < 2; ++k) \
;         acc[ai][bj][m][n] = __builtin_amdgcn_mfma_f32_16x16x32_bf16(Bt[n][k], At[m][k], acc[ai][bj][m][n], 0, 0, 0); __builtin_amdgcn_s_setprio(0); } while (0)
; #define PG8_WAIT_V(n) asm volatile("s_waitcnt vmcnt(" #n ")" ::: "memory")
; #define PG8_WAIT_L(n) asm volatile("s_waitcnt lgkmcnt(" #n ")" ::: "memory")
; #define PG8_BAR __builtin_amdgcn_s_barrier()
; #define PG8_SCHED __builtin_amdgcn_sched_barrier(0)
; template <class Epi, class Sched, bool ALIGN_EPI = false, bool SP2 = false>
; __device__ __forceinline__ void gemm_phase(LAS unsigned char* lds, const Gemm g, const Sched& S, const Epi& E) {
;     ...
;             PG8_LDA(At, 1, 1); PG8_STAGE(PG8_SB(1, 0), b3, voffB); PG8_STAGE(PG8_SB(1, 1), b3 + hstep, voffB); PG8_STAGE(PG8_SA(1, 0), a3, voffA);
;             PG8_WAIT_V(8); PG8_WAIT_L(0); PG8_BAR; PG8_MMA(1, 0, At, B0); PG8_MMA(1, 1, At, B1); PG8_BAR; PG8_SCHED;
	ds_read_b128 v[188:191], v155 offset:49152
	ds_read_b128 v[192:195], v155 offset:50176
	ds_read_b128 v[196:199], v155 offset:51200
	ds_read_b128 v[200:203], v155 offset:52224
	ds_read_b128 v[204:207], v155 offset:53248
	ds_read_b128 v[208:211], v155 offset:54272
	ds_read_b128 v[212:215], v155 offset:55296
	ds_read_b128 v[216:219], v155 offset:56320
	s_add_u32 s10, s46, 0x80
	s_addc_u32 s11, s47, 0
	s_mov_b32 m0, s65
	s_nop 0
	global_load_lds_dwordx4 v148, s[10:11]
	s_nop 0
	s_mov_b32 m0, s66
	s_nop 0
	global_load_lds_dwordx4 v150, s[10:11]
	s_add_u32 s10, s46, 0x40080
	s_addc_u32 s11, s47, 0
	s_mov_b32 m0, s69
	s_nop 0
	global_load_lds_dwordx4 v148, s[10:11]
	s_nop 0
	s_mov_b32 m0, s70
	s_nop 0
	global_load_lds_dwordx4 v150, s[10:11]
	s_mov_b32 m0, s67
	s_nop 0
	global_load_lds_dwordx4 v0, s[82:83]
	s_nop 0
	s_mov_b32 m0, s68
	s_nop 0
	global_load_lds_dwordx4 v149, s[82:83]
	s_waitcnt vmcnt(8)
	s_waitcnt lgkmcnt(0)
	s_barrier
	s_setprio 1
	s_waitcnt lgkmcnt(7)
	v_mfma_f32_16x16x32_bf16 v[62:65], v[132:135], v[188:191], v[62:65]
	v_mfma_f32_16x16x32_bf16 v[58:61], v[142:145], v[188:191], v[58:61]
	s_waitcnt lgkmcnt(5)
	v_mfma_f32_16x16x32_bf16 v[54:57], v[132:135], v[196:199], v[54:57]
	v_mfma_f32_16x16x32_bf16 v[46:49], v[142:145], v[196:199], v[46:49]
	s_waitcnt lgkmcnt(3)
	v_mfma_f32_16x16x32_bf16 v[38:41], v[132:135], v[204:207], v[38:41]
	v_mfma_f32_16x16x32_bf16 v[30:33], v[142:145], v[204:207], v[30:33]
	s_waitcnt lgkmcnt(1)
	v_mfma_f32_16x16x32_bf16 v[22:25], v[132:135], v[212:215], v[22:25]
	v_mfma_f32_16x16x32_bf16 v[14:17], v[142:145], v[212:215], v[14:17]
	v_mfma_f32_16x16x32_bf16 v[62:65], v[136:139], v[192:195], v[62:65]
	v_mfma_f32_16x16x32_bf16 v[58:61], v[168:171], v[192:195], v[58:61]
	v_mfma_f32_16x16x32_bf16 v[54:57], v[136:139], v[200:203], v[54:57]
	v_mfma_f32_16x16x32_bf16 v[46:49], v[168:171], v[200:203], v[46:49]
	v_mfma_f32_16x16x32_bf16 v[38:41], v[136:139], v[208:211], v[38:41]
	v_mfma_f32_16x16x32_bf16 v[30:33], v[168:171], v[208:211], v[30:33]
	s_waitcnt lgkmcnt(0)
	v_mfma_f32_16x16x32_bf16 v[22:25], v[136:139], v[216:219], v[22:25]
	v_mfma_f32_16x16x32_bf16 v[14:17], v[168:171], v[216:219], v[14:17]
	s_setprio 0
	s_setprio 1
	v_mfma_f32_16x16x32_bf16 v[50:53], v[172:175], v[188:191], v[50:53]
	v_mfma_f32_16x16x32_bf16 v[42:45], v[180:183], v[188:191], v[42:45]
	v_mfma_f32_16x16x32_bf16 v[34:37], v[172:175], v[196:199], v[34:37]
	v_mfma_f32_16x16x32_bf16 v[26:29], v[180:183], v[196:199], v[26:29]
	v_mfma_f32_16x16x32_bf16 v[18:21], v[172:175], v[204:207], v[18:21]
	v_mfma_f32_16x16x32_bf16 v[10:13], v[180:183], v[204:207], v[10:13]
	v_mfma_f32_16x16x32_bf16 v[6:9], v[172:175], v[212:215], v[6:9]
	v_mfma_f32_16x16x32_bf16 v[2:5], v[180:183], v[212:215], v[2:5]
	v_mfma_f32_16x16x32_bf16 v[50:53], v[176:179], v[192:195], v[50:53]
	v_mfma_f32_16x16x32_bf16 v[42:45], v[184:187], v[192:195], v[42:45]
	v_mfma_f32_16x16x32_bf16 v[34:37], v[176:179], v[200:203], v[34:37]
	v_mfma_f32_16x16x32_bf16 v[26:29], v[184:187], v[200:203], v[26:29]
	v_mfma_f32_16x16x32_bf16 v[18:21], v[176:179], v[208:211], v[18:21]
	v_mfma_f32_16x16x32_bf16 v[10:13], v[184:187], v[208:211], v[10:13]
	v_mfma_f32_16x16x32_bf16 v[6:9], v[176:179], v[216:219], v[6:9]
	v_mfma_f32_16x16x32_bf16 v[2:5], v[184:187], v[216:219], v[2:5]
	s_setprio 0
	s_barrier
	s_add_i32 s77, s77, 2
	s_add_u32 s75, s75, 0x100
	s_addc_u32 s76, s76, 0
	s_cmp_gt_u32 s77, 13
	s_mov_b64 s[22:23], vcc
	s_cbranch_scc0 .LBB0_117
	s_and_b64 vcc, exec, s[90:91]
	s_cbranch_vccz .LBB0_120
